# grid barrier after pass 2: XCD leader skips the L2 write-back (that phase stores only write-through data)
# speedup vs baseline: 1.0019x; 1.0019x over previous
.LBB0_612:
	s_andn2_saveexec_b64 s[2:3], s[2:3]
	s_cbranch_execz .LBB0_22
	s_mov_b64 s[2:3], exec
	s_cmp_eq_u32 s70, 4
	s_cbranch_scc1 .Lnowb
	s_cmp_eq_u32 s70, 11
	s_cbranch_scc1 .Lnowb
	buffer_wbl2 sc1
.Lnowb:
	s_waitcnt lgkmcnt(0)
	s_waitcnt vmcnt(0)
	v_mbcnt_lo_u32_b32 v1, s2, 0
	v_mbcnt_hi_u32_b32 v1, s3, v1
	v_cmp_eq_u32_e32 vcc, 0, v1
	s_and_saveexec_b64 s[6:7], vcc
	s_cbranch_execz .LBB0_615
	s_bcnt1_i32_b64 s2, s[2:3]
	v_mov_b32_e32 v2, s2
	v_readlane_b32 s2, v255, 32
	v_readlane_b32 s3, v255, 33
	s_nop 4
	global_atomic_add v2, v177, v2, s[2:3] sc0
